# gating: next-head u prefetch as 4 dwordx4 (64-byte runs, permlane16_swap unshuffle), bias prefetch, W-fragment build waits relaxed
# speedup vs baseline: 1.0063x; 1.0063x over previous
.Lgat_st_end:
	s_or_b64 exec, exec, s[100:101]
	s_add_i32 s0, 0, 0x11000
	v_lshl_add_u32 v48, v54, 2, s0
	v_bitop3_b32 v53, v53, -4, 4 bitop3:0xc8
	v_ashrrev_i32_e32 v56, 4, v52
	s_waitcnt lgkmcnt(0)
	s_barrier
	v_add_u32_e32 v53, s0, v53
	ds_read_b32 v124, v48
	ds_read_b64 v[92:93], v48 offset:512
	ds_read_b32 v125, v53
	v_and_b32_e32 v48, 48, v58
	v_and_b32_e32 v62, 15, v52
	s_lshl_b32 s0, s88, 4
	v_lshlrev_b32_e32 v54, 3, v56
	v_bitop3_b32 v48, v60, v48, -2 bitop3:0x6c
	v_or_b32_e32 v53, s0, v62
	v_lshlrev_b32_e32 v127, 1, v48
	v_or_b32_e32 v48, 2, v54
	v_cmp_gt_i32_e64 s[6:7], v48, v53
	v_or_b32_e32 v48, 3, v54
	v_cmp_gt_i32_e64 s[8:9], v48, v53
	v_or_b32_e32 v48, 4, v54
	v_cmp_gt_i32_e64 s[10:11], v48, v53
	v_or_b32_e32 v48, 5, v54
	v_cmp_gt_i32_e64 s[12:13], v48, v53
	v_or_b32_e32 v48, 6, v54
	v_cmp_gt_i32_e64 s[14:15], v48, v53
	v_or_b32_e32 v48, 7, v54
	v_cmp_gt_i32_e64 s[16:17], v48, v53
	v_add_u32_e32 v48, 32, v54
	v_cmp_gt_i32_e64 s[18:19], v48, v53
	v_add_u32_e32 v48, 33, v54
	v_cmp_gt_i32_e64 s[20:21], v48, v53
	v_add_u32_e32 v48, 34, v54
	v_cmp_gt_i32_e64 s[22:23], v48, v53
	v_add_u32_e32 v48, 35, v54
	v_cmp_gt_i32_e64 s[24:25], v48, v53
	v_add_u32_e32 v48, 36, v54
	v_cmp_gt_i32_e64 s[26:27], v48, v53
	v_add_u32_e32 v48, 37, v54
	v_cmp_gt_i32_e64 s[28:29], v48, v53
	v_add_u32_e32 v48, 38, v54
	v_cmp_gt_i32_e64 s[30:31], v48, v53
	v_add_u32_e32 v48, 39, v54
	v_cmp_gt_i32_e64 s[34:35], v48, v53
	v_add_u32_e32 v48, 64, v54
	v_cmp_gt_i32_e64 s[36:37], v48, v53
	v_add_u32_e32 v48, 0x41, v54
	v_cmp_gt_i32_e64 s[38:39], v48, v53
	v_add_u32_e32 v48, 0x42, v54
	v_cmp_gt_i32_e64 s[40:41], v48, v53
	v_add_u32_e32 v48, 0x43, v54
	v_cmp_gt_i32_e64 s[42:43], v48, v53
	v_add_u32_e32 v48, 0x44, v54
	v_cmp_gt_i32_e64 s[44:45], v48, v53
	v_add_u32_e32 v48, 0x45, v54
	s_cmpk_gt_u32 s33, 0x7f
	v_cmp_gt_i32_e64 s[46:47], v48, v53
	v_add_u32_e32 v48, 0x46, v54
	s_cselect_b64 s[76:77], -1, 0
	s_cmpk_gt_u32 s33, 0xff
	v_cmp_gt_i32_e64 s[48:49], v48, v53
	v_add_u32_e32 v48, 0x47, v54
	s_cselect_b64 s[78:79], -1, 0
	s_cmpk_gt_u32 s33, 0x17f
	v_cmp_gt_i32_e64 s[50:51], v48, v53
	v_add_u32_e32 v48, 0x60, v54
	s_cselect_b64 s[80:81], -1, 0
	v_cmp_gt_i32_e64 s[52:53], v48, v53
	v_add_u32_e32 v48, 0x61, v54
	s_bfe_u32 s82, s60, 0x20003
	v_cmp_gt_i32_e64 s[54:55], v48, v53
	v_add_u32_e32 v48, 0x62, v54
	s_lshl_b32 s60, s82, 9
	v_cmp_gt_i32_e64 s[56:57], v48, v53
	v_add_u32_e32 v48, 0x63, v54
	s_add_i32 s60, s60, s0
	v_cmp_gt_i32_e64 s[58:59], v48, v53
	v_or_b32_e32 v48, s60, v62
	v_lshl_add_u64 v[94:95], v[48:49], 2, s[62:63]
	s_lshl_b32 s62, s66, 10
	s_lshl_b32 s63, s64, 7
	v_add_u32_e32 v58, 0x64, v54
	s_add_i32 s64, s62, s63
	v_cmp_gt_i32_e64 s[60:61], v58, v53
	v_add_u32_e32 v58, 0x65, v54
	s_add_i32 s64, s64, s0
	v_cmp_gt_i32_e64 s[62:63], v58, v53
	v_or_b32_e32 v58, s64, v62
	v_lshlrev_b32_e32 v56, 2, v56
	v_mul_u32_u24_e32 v126, 0x110, v59
	v_ashrrev_i32_e32 v59, 31, v58
	v_ashrrev_i32_e32 v57, 31, v56
	s_lshl_b32 s64, s66, 24
	s_mov_b32 s65, s1
	v_lshlrev_b64 v[60:61], 12, v[58:59]
	v_lshl_add_u64 v[60:61], s[64:65], 0, v[60:61]
	v_lshlrev_b64 v[56:57], 1, v[56:57]
	v_lshl_add_u64 v[60:61], v[60:61], 0, v[56:57]
	v_lshl_add_u64 v[60:61], s[94:95], 0, v[60:61]
	s_mov_b64 s[64:65], 0x13800080
	s_movk_i32 s67, 0x60
	v_lshl_add_u64 v[96:97], v[60:61], 0, s[64:65]
	v_lshlrev_b64 v[58:59], 13, v[58:59]
	v_mov_b32_e32 v60, 0xc00000
	v_mad_u64_u32 v[58:59], s[64:65], s66, v60, v[58:59]
	v_bitop3_b32 v128, v52, s67, -16 bitop3:0x6c
	v_mad_u64_u32 v[50:51], s[66:67], s66, v60, v[50:51]
	v_and_b32_e32 v130, -16, v52
	v_bitop3_b32 v131, v52, 32, -16 bitop3:0x6c
	v_bitop3_b32 v132, v52, 64, -16 bitop3:0x6c
	v_and_b32_e32 v52, 7, v52
	v_lshl_add_u64 v[56:57], v[58:59], 0, v[56:57]
	v_lshl_or_b32 v50, v52, 5, v50
	v_ashrrev_i32_e32 v55, 31, v54
	v_lshl_add_u64 v[56:57], s[94:95], 0, v[56:57]
	s_mov_b64 s[64:65], 0x13000080
	v_lshl_add_u64 v[100:101], s[94:95], 0, v[50:51]
	v_mov_b32_e32 v51, v49
	v_lshlrev_b64 v[48:49], 9, v[48:49]
	v_add_u32_e32 v63, 0x66, v54
	v_lshl_add_u64 v[98:99], v[56:57], 0, s[64:65]
	v_add_u32_e32 v56, 0x67, v54
	v_lshlrev_b32_e32 v50, 6, v52
	v_lshl_add_u64 v[48:49], v[54:55], 2, v[48:49]
	v_cmp_gt_i32_e64 s[2:3], v54, v53
	v_cmp_lt_i32_e64 s[4:5], v54, v53
	v_cmp_gt_i32_e64 s[64:65], v63, v53
	v_cmp_gt_i32_e64 s[66:67], v56, v53
	v_add_u32_e32 v53, 64, v130
	v_add_u32_e32 v56, 0xc0, v130
	s_lshl_b32 s0, s82, 10
	v_lshl_or_b32 v50, s82, 11, v50
	v_lshl_add_u64 v[48:49], s[72:73], 0, v[48:49]
	s_mov_b64 s[82:83], 0x100
	s_mov_b64 s[74:75], 0
	s_mov_b32 s96, s88
	v_mul_u32_u24_e32 v129, 0x110, v62
	v_xor_b32_e32 v133, 64, v53
	v_xor_b32_e32 v134, 64, v56
	v_xor_b32_e32 v135, 0x60, v53
	v_xor_b32_e32 v136, 0x60, v56
	v_lshl_add_u64 v[102:103], s[70:71], 0, v[50:51]
	v_lshl_add_u64 v[104:105], v[48:49], 0, s[82:83]
	v_lshl_add_u64 v[106:107], s[68:69], 0, v[50:51]
	s_mov_b32 s84, 0xffff0000
	s_movk_i32 s85, 0x7fff
	s_mov_b32 s88, s1
	v_lshl_add_u64 v[76:77], v[94:95], 0, s[74:75]
	global_load_dword v137, v[76:77], off
	v_lshl_add_u64 v[76:77], v[98:99], 0, s[0:1]
	global_load_dwordx2 v[122:123], v[76:77], off offset:-128
	global_load_dwordx2 v[120:121], v[76:77], off offset:-96
	global_load_dwordx2 v[118:119], v[76:77], off offset:-64
	global_load_dwordx2 v[116:117], v[76:77], off offset:-32
	global_load_dwordx2 v[114:115], v[76:77], off
	global_load_dwordx2 v[112:113], v[76:77], off offset:32
	global_load_dwordx2 v[110:111], v[76:77], off offset:64
	global_load_dwordx2 v[108:109], v[76:77], off offset:96
	v_mbcnt_lo_u32_b32 v148, -1, 0
	v_mbcnt_hi_u32_b32 v148, -1, v148
	v_lshrrev_b32_e32 v148, 4, v148
	v_and_b32_e32 v148, 1, v148
	v_mul_u32_u24_e32 v148, 24, v148
	v_mov_b32_e32 v149, 0
	s_waitcnt vmcnt(9)
	s_branch .Lgat_top2

.LBB0_507:
	v_permlane16_swap_b32_e32 v192, v194
	v_permlane16_swap_b32_e32 v193, v195
	v_permlane16_swap_b32_e32 v196, v198
	v_permlane16_swap_b32_e32 v197, v199
	v_permlane16_swap_b32_e32 v200, v202
	v_permlane16_swap_b32_e32 v201, v203
	v_permlane16_swap_b32_e32 v204, v206
	v_permlane16_swap_b32_e32 v205, v207
	v_mov_b32_e32 v122, v192
	v_mov_b32_e32 v123, v193
	v_mov_b32_e32 v120, v194
	v_mov_b32_e32 v121, v195
	v_mov_b32_e32 v118, v196
	v_mov_b32_e32 v119, v197
	v_mov_b32_e32 v116, v198
	v_mov_b32_e32 v117, v199
	v_mov_b32_e32 v114, v200
	v_mov_b32_e32 v115, v201
	v_mov_b32_e32 v112, v202
	v_mov_b32_e32 v113, v203
	v_mov_b32_e32 v110, v204
	v_mov_b32_e32 v111, v205
	v_mov_b32_e32 v108, v206
	v_mov_b32_e32 v109, v207
	v_mov_b32_e32 v137, v208

.LBB0_511:
	s_cmp_lg_u32 s74, 0x600
	s_cselect_b32 s98, 0x200, 0
	s_cselect_b32 s100, s82, 0
	s_cselect_b32 s101, s83, 0
	s_add_u32 s98, s74, s98
	s_addc_u32 s99, s75, 0
	v_lshl_add_u64 v[76:77], v[94:95], 0, s[98:99]
	global_load_dword v208, v[76:77], off
	v_lshl_add_u64 v[76:77], v[98:99], 0, s[0:1]
	v_lshl_add_u64 v[76:77], v[76:77], 0, s[100:101]
	v_lshl_add_u64 v[76:77], v[76:77], 0, v[148:149]
	global_load_dwordx4 v[192:195], v[76:77], off offset:-128
	global_load_dwordx4 v[196:199], v[76:77], off offset:-64
	global_load_dwordx4 v[200:203], v[76:77], off
	global_load_dwordx4 v[204:207], v[76:77], off offset:64
	s_waitcnt vmcnt(22)
	v_lshlrev_b32_e32 v77, 16, v0
	s_bitcmp1_b32 s88, 0
	s_waitcnt lgkmcnt(2)
	v_sub_f32_e32 v77, v77, v124
	s_waitcnt vmcnt(20)
	v_lshlrev_b32_e32 v78, 16, v8
	s_cselect_b32 s89, 0x8800, 0
	s_waitcnt lgkmcnt(1)
	v_mul_f32_e32 v77, v92, v77
	s_waitcnt lgkmcnt(0)
	v_sub_f32_e32 v78, v78, v125
	s_add_i32 s89, s89, 0
	s_waitcnt vmcnt(11)
	v_fma_f32 v77, v28, v77, v44
	v_mul_f32_e32 v78, v93, v78
	v_add3_u32 v76, s89, v126, v127
	v_fma_f32 v78, v28, v78, v44
	v_cvt_pk_bf16_f32 v77, v77, v78
	ds_write_b32 v76, v77
	v_and_b32_e32 v77, 0xffff0000, v0
	v_sub_f32_e32 v77, v77, v124
	v_and_b32_e32 v78, 0xffff0000, v8
	v_mul_f32_e32 v77, v92, v77
	v_sub_f32_e32 v78, v78, v125
	v_fma_f32 v77, v29, v77, v45
	v_mul_f32_e32 v78, v93, v78
	v_fma_f32 v78, v29, v78, v45
	v_cvt_pk_bf16_f32 v77, v77, v78
	ds_write_b32 v76, v77 offset:272
	v_lshlrev_b32_e32 v77, 16, v1
	v_sub_f32_e32 v77, v77, v124
	v_lshlrev_b32_e32 v78, 16, v9
	v_mul_f32_e32 v77, v92, v77
	v_sub_f32_e32 v78, v78, v125
	v_fma_f32 v77, v30, v77, v46
	v_mul_f32_e32 v78, v93, v78
	v_fma_f32 v78, v30, v78, v46
	v_cvt_pk_bf16_f32 v77, v77, v78
	ds_write_b32 v76, v77 offset:544
	v_and_b32_e32 v77, 0xffff0000, v1
	v_sub_f32_e32 v77, v77, v124
	v_and_b32_e32 v78, 0xffff0000, v9
	v_mul_f32_e32 v77, v92, v77
	v_sub_f32_e32 v78, v78, v125
	v_fma_f32 v77, v31, v77, v47
	v_mul_f32_e32 v78, v93, v78
	v_fma_f32 v78, v31, v78, v47
	v_cvt_pk_bf16_f32 v77, v77, v78
	ds_write_b32 v76, v77 offset:816
	v_lshlrev_b32_e32 v77, 16, v2
	v_sub_f32_e32 v77, v77, v124
	v_lshlrev_b32_e32 v78, 16, v10
	v_mul_f32_e32 v77, v92, v77
	v_sub_f32_e32 v78, v78, v125
	v_fma_f32 v77, v24, v77, v40
	v_mul_f32_e32 v78, v93, v78
	v_fma_f32 v78, v24, v78, v40
	v_cvt_pk_bf16_f32 v77, v77, v78
	ds_write_b32 v76, v77 offset:1088
	v_and_b32_e32 v77, 0xffff0000, v2
	v_sub_f32_e32 v77, v77, v124
	v_and_b32_e32 v78, 0xffff0000, v10
	v_mul_f32_e32 v77, v92, v77
	v_sub_f32_e32 v78, v78, v125
	v_fma_f32 v77, v25, v77, v41
	v_mul_f32_e32 v78, v93, v78
	v_fma_f32 v78, v25, v78, v41
	v_cvt_pk_bf16_f32 v77, v77, v78
	ds_write_b32 v76, v77 offset:1360
	v_lshlrev_b32_e32 v77, 16, v3
	v_sub_f32_e32 v77, v77, v124
	v_lshlrev_b32_e32 v78, 16, v11
	v_mul_f32_e32 v77, v92, v77
	v_sub_f32_e32 v78, v78, v125
	v_fma_f32 v77, v26, v77, v42
	v_mul_f32_e32 v78, v93, v78
	v_fma_f32 v78, v26, v78, v42
	v_cvt_pk_bf16_f32 v77, v77, v78
	ds_write_b32 v76, v77 offset:1632
	v_and_b32_e32 v77, 0xffff0000, v3
	v_sub_f32_e32 v77, v77, v124
	v_and_b32_e32 v78, 0xffff0000, v11
	v_mul_f32_e32 v77, v92, v77
	v_sub_f32_e32 v78, v78, v125
	v_fma_f32 v77, v27, v77, v43
	v_mul_f32_e32 v78, v93, v78
	v_fma_f32 v78, v27, v78, v43
	v_cvt_pk_bf16_f32 v77, v77, v78
	ds_write_b32 v76, v77 offset:1904
	v_lshlrev_b32_e32 v77, 16, v4
	v_sub_f32_e32 v77, v77, v124
	v_lshlrev_b32_e32 v78, 16, v12
	v_mul_f32_e32 v77, v92, v77
	v_sub_f32_e32 v78, v78, v125
	v_fma_f32 v77, v20, v77, v36
	v_mul_f32_e32 v78, v93, v78
	v_fma_f32 v78, v20, v78, v36
	v_cvt_pk_bf16_f32 v77, v77, v78
	ds_write_b32 v76, v77 offset:2176
	v_and_b32_e32 v77, 0xffff0000, v4
	v_sub_f32_e32 v77, v77, v124
	v_and_b32_e32 v78, 0xffff0000, v12
	v_mul_f32_e32 v77, v92, v77
	v_sub_f32_e32 v78, v78, v125
	v_fma_f32 v77, v21, v77, v37
	v_mul_f32_e32 v78, v93, v78
	v_fma_f32 v78, v21, v78, v37
	v_cvt_pk_bf16_f32 v77, v77, v78
	ds_write_b32 v76, v77 offset:2448
	v_lshlrev_b32_e32 v77, 16, v5
	v_sub_f32_e32 v77, v77, v124
	v_lshlrev_b32_e32 v78, 16, v13
	v_mul_f32_e32 v77, v92, v77
	v_sub_f32_e32 v78, v78, v125
	v_fma_f32 v77, v22, v77, v38
	v_mul_f32_e32 v78, v93, v78
	v_fma_f32 v78, v22, v78, v38
	v_cvt_pk_bf16_f32 v77, v77, v78
	ds_write_b32 v76, v77 offset:2720
	v_and_b32_e32 v77, 0xffff0000, v5
	v_sub_f32_e32 v77, v77, v124
	v_and_b32_e32 v78, 0xffff0000, v13
	v_mul_f32_e32 v77, v92, v77
	v_sub_f32_e32 v78, v78, v125
	v_fma_f32 v77, v23, v77, v39
	v_mul_f32_e32 v78, v93, v78
	v_fma_f32 v78, v23, v78, v39
	v_cvt_pk_bf16_f32 v77, v77, v78
	ds_write_b32 v76, v77 offset:2992
	v_lshlrev_b32_e32 v77, 16, v6
	v_sub_f32_e32 v77, v77, v124
	v_lshlrev_b32_e32 v78, 16, v14
	v_mul_f32_e32 v77, v92, v77
	v_sub_f32_e32 v78, v78, v125
	v_fma_f32 v77, v16, v77, v32
	v_mul_f32_e32 v78, v93, v78
	v_fma_f32 v78, v16, v78, v32
	v_cvt_pk_bf16_f32 v77, v77, v78
	ds_write_b32 v76, v77 offset:3264
	v_and_b32_e32 v77, 0xffff0000, v6
	v_sub_f32_e32 v77, v77, v124
	v_and_b32_e32 v78, 0xffff0000, v14
	v_mul_f32_e32 v77, v92, v77
	v_sub_f32_e32 v78, v78, v125
	v_fma_f32 v77, v17, v77, v33
	v_mul_f32_e32 v78, v93, v78
	v_fma_f32 v78, v17, v78, v33
	v_cvt_pk_bf16_f32 v77, v77, v78
	ds_write_b32 v76, v77 offset:3536
	v_lshlrev_b32_e32 v77, 16, v7
	v_sub_f32_e32 v77, v77, v124
	v_lshlrev_b32_e32 v78, 16, v15
	v_mul_f32_e32 v77, v92, v77
	v_sub_f32_e32 v78, v78, v125
	v_fma_f32 v77, v18, v77, v34
	v_mul_f32_e32 v78, v93, v78
	v_fma_f32 v78, v18, v78, v34
	v_cvt_pk_bf16_f32 v77, v77, v78
	ds_write_b32 v76, v77 offset:3808
	v_and_b32_e32 v77, 0xffff0000, v7
	v_sub_f32_e32 v77, v77, v124
	v_and_b32_e32 v78, 0xffff0000, v15
	v_mul_f32_e32 v77, v92, v77
	v_sub_f32_e32 v78, v78, v125
	v_fma_f32 v77, v19, v77, v35
	v_mul_f32_e32 v78, v93, v78
	s_cmpk_eq_i32 s74, 0x600
	v_fma_f32 v78, v19, v78, v35
	v_cvt_pk_bf16_f32 v77, v77, v78
	ds_write_b32 v76, v77 offset:4080
	s_cbranch_scc1 .LBB0_513
	v_lshl_add_u64 v[8:9], v[100:101], 0, s[0:1]
	s_mov_b64 s[90:91], 0x13001100
	v_add_co_u32_e32 v0, vcc, 0x13001000, v8
	v_lshl_add_u64 v[4:5], v[8:9], 0, s[90:91]
	s_nop 0
	v_addc_co_u32_e32 v1, vcc, 0, v9, vcc
	s_mov_b64 s[90:91], 0x13003100
	v_lshl_add_u64 v[12:13], v[8:9], 0, s[90:91]
	v_add_co_u32_e32 v8, vcc, 0x13003000, v8
	v_lshl_add_u64 v[28:29], v[102:103], 0, s[74:75]
	s_nop 0
	v_addc_co_u32_e32 v9, vcc, 0, v9, vcc
	v_lshl_add_u64 v[44:45], v[106:107], 0, s[74:75]
	global_load_dwordx4 v[0:3], v[0:1], off offset:256
	s_nop 0
	global_load_dwordx4 v[4:7], v[4:5], off offset:16
	s_nop 0
	global_load_dwordx4 v[8:11], v[8:9], off offset:256
	s_nop 0
	global_load_dwordx4 v[12:15], v[12:13], off offset:16
	s_nop 0
	global_load_dwordx4 v[16:19], v[28:29], off offset:560
	global_load_dwordx4 v[20:23], v[28:29], off offset:544
	global_load_dwordx4 v[24:27], v[28:29], off offset:528
	s_nop 0
	global_load_dwordx4 v[28:31], v[28:29], off offset:512
	s_nop 0
	global_load_dwordx4 v[32:35], v[44:45], off offset:560
	global_load_dwordx4 v[36:39], v[44:45], off offset:544
	global_load_dwordx4 v[40:43], v[44:45], off offset:528
	s_nop 0
	global_load_dwordx4 v[44:47], v[44:45], off offset:512
	v_readlane_b32 s90, v252, 6
	v_readlane_b32 s91, v252, 7
.LBB0_513:
	s_and_b64 vcc, exec, s[68:69]
	s_waitcnt lgkmcnt(0)
	s_barrier
	s_cbranch_vccnz .LBB0_519
	s_waitcnt vmcnt(5)
	v_cndmask_b32_e64 v76, v68, 0, s[18:19]
	v_bfe_u32 v77, v76, 16, 1
	v_add3_u32 v76, v76, v77, s85
	v_cndmask_b32_e64 v77, v69, 0, s[20:21]
	v_bfe_u32 v78, v77, 16, 1
	v_lshrrev_b32_e32 v76, 16, v76
	v_add3_u32 v77, v77, v78, s85
	v_and_or_b32 v76, v77, s84, v76
	v_cndmask_b32_e64 v77, v70, 0, s[22:23]
	v_bfe_u32 v78, v77, 16, 1
	v_add3_u32 v77, v77, v78, s85
	v_cndmask_b32_e64 v78, v71, 0, s[24:25]
	v_bfe_u32 v79, v78, 16, 1
	v_lshrrev_b32_e32 v77, 16, v77
	v_add3_u32 v78, v78, v79, s85
	v_and_or_b32 v77, v78, s84, v77
	v_cndmask_b32_e64 v78, v60, 0, s[26:27]
	v_bfe_u32 v79, v78, 16, 1
	v_add3_u32 v78, v78, v79, s85
	v_cndmask_b32_e64 v79, v61, 0, s[28:29]
	v_bfe_u32 v84, v79, 16, 1
	v_lshrrev_b32_e32 v78, 16, v78
	v_add3_u32 v79, v79, v84, s85
	v_and_or_b32 v78, v79, s84, v78
	v_cndmask_b32_e64 v79, v62, 0, s[30:31]
	v_bfe_u32 v84, v79, 16, 1
	v_add3_u32 v79, v79, v84, s85
	v_cndmask_b32_e64 v84, v63, 0, s[34:35]
	v_bfe_u32 v85, v84, 16, 1
	v_lshrrev_b32_e32 v79, 16, v79
	v_add3_u32 v84, v84, v85, s85
	v_and_or_b32 v79, v84, s84, v79
	s_and_b64 vcc, exec, s[70:71]
	s_cbranch_vccz .LBB0_520

.LBB0_520:
	s_waitcnt vmcnt(5)
	v_cndmask_b32_e64 v84, v64, 0, s[36:37]
	v_bfe_u32 v85, v84, 16, 1
	v_add3_u32 v84, v84, v85, s85
	v_cndmask_b32_e64 v85, v65, 0, s[38:39]
	v_bfe_u32 v86, v85, 16, 1
	v_lshrrev_b32_e32 v84, 16, v84
	v_add3_u32 v85, v85, v86, s85
	v_and_or_b32 v84, v85, s84, v84
	v_cndmask_b32_e64 v85, v66, 0, s[40:41]
	v_bfe_u32 v86, v85, 16, 1
	v_add3_u32 v85, v85, v86, s85
	v_cndmask_b32_e64 v86, v67, 0, s[42:43]
	v_bfe_u32 v87, v86, 16, 1
	v_lshrrev_b32_e32 v85, 16, v85
	v_add3_u32 v86, v86, v87, s85
	v_and_or_b32 v85, v86, s84, v85
	v_cndmask_b32_e64 v86, v52, 0, s[44:45]
	v_bfe_u32 v87, v86, 16, 1
	v_add3_u32 v86, v86, v87, s85
	v_cndmask_b32_e64 v87, v53, 0, s[46:47]
	v_bfe_u32 v88, v87, 16, 1
	v_lshrrev_b32_e32 v86, 16, v86
	v_add3_u32 v87, v87, v88, s85
	v_and_or_b32 v86, v87, s84, v86
	v_cndmask_b32_e64 v87, v54, 0, s[48:49]
	v_bfe_u32 v88, v87, 16, 1
	v_add3_u32 v87, v87, v88, s85
	v_cndmask_b32_e64 v88, v55, 0, s[50:51]
	v_bfe_u32 v89, v88, 16, 1
	v_lshrrev_b32_e32 v87, 16, v87
	v_add3_u32 v88, v88, v89, s85
	v_and_or_b32 v87, v88, s84, v87
	s_and_b64 vcc, exec, s[72:73]
	s_cbranch_vccnz .LBB0_516
.LBB0_521:
	s_waitcnt vmcnt(5)
	v_cndmask_b32_e64 v88, v56, 0, s[52:53]
	v_bfe_u32 v89, v88, 16, 1
	v_add3_u32 v88, v88, v89, s85
	v_cndmask_b32_e64 v89, v57, 0, s[54:55]
	v_bfe_u32 v90, v89, 16, 1
	v_lshrrev_b32_e32 v88, 16, v88
	v_add3_u32 v89, v89, v90, s85
	v_and_or_b32 v88, v89, s84, v88
	v_cndmask_b32_e64 v89, v58, 0, s[56:57]
	v_bfe_u32 v90, v89, 16, 1
	v_add3_u32 v89, v89, v90, s85
	v_cndmask_b32_e64 v90, v59, 0, s[58:59]
	v_bfe_u32 v91, v90, 16, 1
	v_lshrrev_b32_e32 v89, 16, v89
	v_add3_u32 v90, v90, v91, s85
	v_and_or_b32 v89, v90, s84, v89
	v_cndmask_b32_e64 v90, v48, 0, s[60:61]
	v_bfe_u32 v91, v90, 16, 1
	v_add3_u32 v90, v90, v91, s85
	v_cndmask_b32_e64 v91, v49, 0, s[62:63]
	v_bfe_u32 v138, v91, 16, 1
	v_lshrrev_b32_e32 v90, 16, v90
	v_add3_u32 v91, v91, v138, s85
	v_and_or_b32 v90, v91, s84, v90
	v_cndmask_b32_e64 v91, v50, 0, s[64:65]
	v_bfe_u32 v138, v91, 16, 1
	v_add3_u32 v91, v91, v138, s85
	v_cndmask_b32_e64 v138, v51, 0, s[66:67]
	v_bfe_u32 v139, v138, 16, 1
	v_lshrrev_b32_e32 v91, 16, v91
	v_add3_u32 v138, v138, v139, s85
	v_and_or_b32 v91, v138, s84, v91
.LBB0_522:
	s_waitcnt vmcnt(5)
	v_cndmask_b32_e64 v80, v80, 0, s[2:3]
	v_bfe_u32 v138, v80, 16, 1
	v_cndmask_b32_e64 v81, 0, v81, s[4:5]
	v_add3_u32 v80, v80, v138, s85
	v_bfe_u32 v138, v81, 16, 1
	v_lshrrev_b32_e32 v80, 16, v80
	v_add3_u32 v81, v81, v138, s85
	v_and_or_b32 v80, v81, s84, v80
	v_cndmask_b32_e64 v81, v82, 0, s[6:7]
	v_bfe_u32 v82, v81, 16, 1
	v_add3_u32 v81, v81, v82, s85
	v_cndmask_b32_e64 v82, v83, 0, s[8:9]
	v_bfe_u32 v83, v82, 16, 1
	v_add_u32_e32 v141, s89, v129
	v_lshrrev_b32_e32 v81, 16, v81
	v_add3_u32 v82, v82, v83, s85
	v_cndmask_b32_e64 v72, v72, 0, s[10:11]
	v_add_u32_e32 v138, v141, v130
	v_and_or_b32 v81, v82, s84, v81
	v_bfe_u32 v82, v72, 16, 1
	v_cndmask_b32_e64 v73, v73, 0, s[12:13]
	v_add3_u32 v72, v72, v82, s85
	v_bfe_u32 v82, v73, 16, 1
	v_lshrrev_b32_e32 v72, 16, v72
	v_add3_u32 v73, v73, v82, s85
	v_and_or_b32 v82, v73, s84, v72
	v_cndmask_b32_e64 v72, v74, 0, s[14:15]
	v_bfe_u32 v73, v72, 16, 1
	v_add3_u32 v72, v72, v73, s85
	v_cndmask_b32_e64 v73, v75, 0, s[16:17]
	v_bfe_u32 v74, v73, 16, 1
	v_lshrrev_b32_e32 v72, 16, v72
	v_add3_u32 v73, v73, v74, s85
	v_and_or_b32 v83, v73, s84, v72
	v_add_u32_e32 v150, v141, v131
	v_add_u32_e32 v151, v141, v132
	v_add_u32_e32 v152, v141, v133
	v_add_u32_e32 v153, v141, v134
	v_add_u32_e32 v154, v141, v128
	v_add_u32_e32 v155, v141, v135
	v_add_u32_e32 v156, v141, v136
	ds_read_b128 v[160:163], v138
	ds_read_b128 v[164:167], v138 offset:64
	ds_read_b128 v[168:171], v138 offset:128
	ds_read_b128 v[172:175], v138 offset:192
	ds_read_b128 v[176:179], v150 offset:4352
	ds_read_b128 v[180:183], v150 offset:4416
	ds_read_b128 v[184:187], v150 offset:4480
	ds_read_b128 v[188:191], v150 offset:4544
	ds_read_b128 v[48:51], v151 offset:8704
	ds_read_b128 v[52:55], v152 offset:8704
	ds_read_b128 v[56:59], v151 offset:8832
	ds_read_b128 v[60:63], v153 offset:8704
	ds_read_b128 v[64:67], v154 offset:13056
	ds_read_b128 v[68:71], v155 offset:13056
	ds_read_b128 v[72:75], v154 offset:13184
	ds_read_b128 v[142:145], v156 offset:13056
	v_mbcnt_lo_u32_b32 v148, -1, 0
	v_mbcnt_hi_u32_b32 v148, -1, v148
	v_lshrrev_b32_e32 v148, 4, v148
	v_and_b32_e32 v148, 1, v148
	v_mul_u32_u24_e32 v148, 24, v148
	v_mov_b32_e32 v149, 0
	v_lshl_add_u64 v[158:159], v[96:97], 0, s[0:1]
	v_lshl_add_u64 v[158:159], v[158:159], 0, v[148:149]
	s_waitcnt lgkmcnt(8)
	v_mfma_f32_16x16x32_bf16 v[224:227], v[160:163], v[80:83], 0
	v_mfma_f32_16x16x32_bf16 v[228:231], v[176:179], v[80:83], 0
	v_mfma_f32_16x16x32_bf16 v[224:227], v[164:167], v[76:79], v[224:227]
	v_mfma_f32_16x16x32_bf16 v[228:231], v[180:183], v[76:79], v[228:231]
	v_mfma_f32_16x16x32_bf16 v[224:227], v[168:171], v[84:87], v[224:227]
	v_mfma_f32_16x16x32_bf16 v[228:231], v[184:187], v[84:87], v[228:231]
	v_mfma_f32_16x16x32_bf16 v[224:227], v[172:175], v[88:91], v[224:227]
	v_mfma_f32_16x16x32_bf16 v[228:231], v[188:191], v[88:91], v[228:231]
	ds_read_b128 v[160:163], v138 offset:17408
	ds_read_b128 v[164:167], v138 offset:17472
	ds_read_b128 v[168:171], v138 offset:17536
	ds_read_b128 v[172:175], v138 offset:17600
	ds_read_b128 v[176:179], v150 offset:21760
	ds_read_b128 v[180:183], v150 offset:21824
	ds_read_b128 v[184:187], v150 offset:21888
	ds_read_b128 v[188:191], v150 offset:21952
	s_waitcnt lgkmcnt(8)
	v_mfma_f32_16x16x32_bf16 v[232:235], v[48:51], v[80:83], 0
	v_mfma_f32_16x16x32_bf16 v[236:239], v[64:67], v[80:83], 0
	v_mfma_f32_16x16x32_bf16 v[232:235], v[52:55], v[76:79], v[232:235]
	v_mfma_f32_16x16x32_bf16 v[236:239], v[68:71], v[76:79], v[236:239]
	v_mfma_f32_16x16x32_bf16 v[232:235], v[56:59], v[84:87], v[232:235]
	v_mfma_f32_16x16x32_bf16 v[236:239], v[72:75], v[84:87], v[236:239]
	v_mfma_f32_16x16x32_bf16 v[232:235], v[60:63], v[88:91], v[232:235]
	v_mfma_f32_16x16x32_bf16 v[236:239], v[142:145], v[88:91], v[236:239]
	ds_read_b128 v[48:51], v151 offset:26112
	ds_read_b128 v[52:55], v152 offset:26112
	ds_read_b128 v[56:59], v151 offset:26240
	ds_read_b128 v[60:63], v153 offset:26112
	ds_read_b128 v[64:67], v154 offset:30464
	ds_read_b128 v[68:71], v155 offset:30464
	ds_read_b128 v[72:75], v154 offset:30592
	ds_read_b128 v[142:145], v156 offset:30464
	v_lshlrev_b32_e32 v248, 16, v122
	v_add_f32_e32 v249, v137, v224
	v_mul_f32_e32 v249, v249, v248
	v_and_b32_e32 v248, 0xffff0000, v122
	v_add_f32_e32 v250, v137, v225
	v_mul_f32_e32 v250, v250, v248
	v_cvt_pk_bf16_f32 v240, v249, v250
	v_lshlrev_b32_e32 v248, 16, v123
	v_add_f32_e32 v249, v137, v226
	v_mul_f32_e32 v249, v249, v248
	v_and_b32_e32 v248, 0xffff0000, v123
	v_add_f32_e32 v250, v137, v227
	v_mul_f32_e32 v250, v250, v248
	v_cvt_pk_bf16_f32 v241, v249, v250
	v_lshlrev_b32_e32 v248, 16, v120
	v_add_f32_e32 v249, v137, v228
	v_mul_f32_e32 v249, v249, v248
	v_and_b32_e32 v248, 0xffff0000, v120
	v_add_f32_e32 v250, v137, v229
	v_mul_f32_e32 v250, v250, v248
	v_cvt_pk_bf16_f32 v242, v249, v250
	v_lshlrev_b32_e32 v248, 16, v121
	v_add_f32_e32 v249, v137, v230
	v_mul_f32_e32 v249, v249, v248
	v_and_b32_e32 v248, 0xffff0000, v121
	v_add_f32_e32 v250, v137, v231
	v_mul_f32_e32 v250, v250, v248
	v_cvt_pk_bf16_f32 v243, v249, v250
	s_nop 1
	v_permlane16_swap_b32_e32 v240, v242
	v_permlane16_swap_b32_e32 v241, v243
	global_store_dwordx4 v[158:159], v[240:243], off offset:-128
	s_waitcnt lgkmcnt(8)
	v_mfma_f32_16x16x32_bf16 v[224:227], v[160:163], v[80:83], 0
	v_mfma_f32_16x16x32_bf16 v[228:231], v[176:179], v[80:83], 0
	v_mfma_f32_16x16x32_bf16 v[224:227], v[164:167], v[76:79], v[224:227]
	v_mfma_f32_16x16x32_bf16 v[228:231], v[180:183], v[76:79], v[228:231]
	v_mfma_f32_16x16x32_bf16 v[224:227], v[168:171], v[84:87], v[224:227]
	v_mfma_f32_16x16x32_bf16 v[228:231], v[184:187], v[84:87], v[228:231]
	v_mfma_f32_16x16x32_bf16 v[224:227], v[172:175], v[88:91], v[224:227]
	v_mfma_f32_16x16x32_bf16 v[228:231], v[188:191], v[88:91], v[228:231]
	v_lshlrev_b32_e32 v248, 16, v118
	v_add_f32_e32 v249, v137, v232
	v_mul_f32_e32 v249, v249, v248
	v_and_b32_e32 v248, 0xffff0000, v118
	v_add_f32_e32 v250, v137, v233
	v_mul_f32_e32 v250, v250, v248
	v_cvt_pk_bf16_f32 v244, v249, v250
	v_lshlrev_b32_e32 v248, 16, v119
	v_add_f32_e32 v249, v137, v234
	v_mul_f32_e32 v249, v249, v248
	v_and_b32_e32 v248, 0xffff0000, v119
	v_add_f32_e32 v250, v137, v235
	v_mul_f32_e32 v250, v250, v248
	v_cvt_pk_bf16_f32 v245, v249, v250
	v_lshlrev_b32_e32 v248, 16, v116
	v_add_f32_e32 v249, v137, v236
	v_mul_f32_e32 v249, v249, v248
	v_and_b32_e32 v248, 0xffff0000, v116
	v_add_f32_e32 v250, v137, v237
	v_mul_f32_e32 v250, v250, v248
	v_cvt_pk_bf16_f32 v246, v249, v250
	v_lshlrev_b32_e32 v248, 16, v117
	v_add_f32_e32 v249, v137, v238
	v_mul_f32_e32 v249, v249, v248
	v_and_b32_e32 v248, 0xffff0000, v117
	v_add_f32_e32 v250, v137, v239
	v_mul_f32_e32 v250, v250, v248
	v_cvt_pk_bf16_f32 v247, v249, v250
	s_nop 1
	v_permlane16_swap_b32_e32 v244, v246
	v_permlane16_swap_b32_e32 v245, v247
	global_store_dwordx4 v[158:159], v[244:247], off offset:-64
	s_waitcnt lgkmcnt(0)
	v_mfma_f32_16x16x32_bf16 v[232:235], v[48:51], v[80:83], 0
	v_mfma_f32_16x16x32_bf16 v[236:239], v[64:67], v[80:83], 0
	v_mfma_f32_16x16x32_bf16 v[232:235], v[52:55], v[76:79], v[232:235]
	v_mfma_f32_16x16x32_bf16 v[236:239], v[68:71], v[76:79], v[236:239]
	v_mfma_f32_16x16x32_bf16 v[232:235], v[56:59], v[84:87], v[232:235]
	v_mfma_f32_16x16x32_bf16 v[236:239], v[72:75], v[84:87], v[236:239]
	v_mfma_f32_16x16x32_bf16 v[232:235], v[60:63], v[88:91], v[232:235]
	v_mfma_f32_16x16x32_bf16 v[236:239], v[142:145], v[88:91], v[236:239]
	v_lshlrev_b32_e32 v248, 16, v114
	v_add_f32_e32 v249, v137, v224
	v_mul_f32_e32 v249, v249, v248
	v_and_b32_e32 v248, 0xffff0000, v114
	v_add_f32_e32 v250, v137, v225
	v_mul_f32_e32 v250, v250, v248
	v_cvt_pk_bf16_f32 v240, v249, v250
	v_lshlrev_b32_e32 v248, 16, v115
	v_add_f32_e32 v249, v137, v226
	v_mul_f32_e32 v249, v249, v248
	v_and_b32_e32 v248, 0xffff0000, v115
	v_add_f32_e32 v250, v137, v227
	v_mul_f32_e32 v250, v250, v248
	v_cvt_pk_bf16_f32 v241, v249, v250
	v_lshlrev_b32_e32 v248, 16, v112
	v_add_f32_e32 v249, v137, v228
	v_mul_f32_e32 v249, v249, v248
	v_and_b32_e32 v248, 0xffff0000, v112
	v_add_f32_e32 v250, v137, v229
	v_mul_f32_e32 v250, v250, v248
	v_cvt_pk_bf16_f32 v242, v249, v250
	v_lshlrev_b32_e32 v248, 16, v113
	v_add_f32_e32 v249, v137, v230
	v_mul_f32_e32 v249, v249, v248
	v_and_b32_e32 v248, 0xffff0000, v113
	v_add_f32_e32 v250, v137, v231
	v_mul_f32_e32 v250, v250, v248
	v_cvt_pk_bf16_f32 v243, v249, v250
	s_nop 1
	v_permlane16_swap_b32_e32 v240, v242
	v_permlane16_swap_b32_e32 v241, v243
	global_store_dwordx4 v[158:159], v[240:243], off offset:0
	s_nop 7
	s_nop 7
	v_lshlrev_b32_e32 v248, 16, v110
	v_add_f32_e32 v249, v137, v232
	v_mul_f32_e32 v249, v249, v248
	v_and_b32_e32 v248, 0xffff0000, v110
	v_add_f32_e32 v250, v137, v233
	v_mul_f32_e32 v250, v250, v248
	v_cvt_pk_bf16_f32 v244, v249, v250
	v_lshlrev_b32_e32 v248, 16, v111
	v_add_f32_e32 v249, v137, v234
	v_mul_f32_e32 v249, v249, v248
	v_and_b32_e32 v248, 0xffff0000, v111
	v_add_f32_e32 v250, v137, v235
	v_mul_f32_e32 v250, v250, v248
	v_cvt_pk_bf16_f32 v245, v249, v250
	v_lshlrev_b32_e32 v248, 16, v108
	v_add_f32_e32 v249, v137, v236
	v_mul_f32_e32 v249, v249, v248
	v_and_b32_e32 v248, 0xffff0000, v108
	v_add_f32_e32 v250, v137, v237
	v_mul_f32_e32 v250, v250, v248
	v_cvt_pk_bf16_f32 v246, v249, v250
	v_lshlrev_b32_e32 v248, 16, v109
	v_add_f32_e32 v249, v137, v238
	v_mul_f32_e32 v249, v249, v248
	v_and_b32_e32 v248, 0xffff0000, v109
	v_add_f32_e32 v250, v137, v239
	v_mul_f32_e32 v250, v250, v248
	v_cvt_pk_bf16_f32 v247, v249, v250
	s_nop 1
	v_permlane16_swap_b32_e32 v244, v246
	v_permlane16_swap_b32_e32 v245, v247
	global_store_dwordx4 v[158:159], v[244:247], off offset:64
	s_waitcnt vmcnt(4)
	s_branch .LBB0_506
